# phase-0 adaLN GEMV: the 16 weight-row loads of each K block issued together behind counted waits instead of one full round trip per row
# speedup vs baseline: 1.0168x; 1.0168x over previous
; #define LAS __attribute__((address_space(3)))
; #define LDS_FENCE() asm volatile("s_waitcnt lgkmcnt(0)" ::: "memory")
; __device__ __forceinline__ void gemv_item(const Params& p, unsigned long long* MOD, int it, LAS float* scr, int lane) {
;     const int mat = it / 1536, rem = it % 1536, cb = rem >> 6, ks = rem & 63, k0 = ks * 32, n0 = cb * 256 + 4 * lane;
; #pragma unroll
;     for (int i = 0; i < 2; ++i) { const int idx = lane + 64 * i, b = idx >> 5, kk = idx & 31; const float cv = p.c[b * DM + k0 + kk]; scr[idx] = cv / (1.0f + __expf(-cv)); }
;     LDS_FENCE();
;     const float* W = p.ada_w + (size_t)mat * DM * 6144 + (size_t)k0 * 6144 + n0;
;     f32x4 a0 = {0, 0, 0, 0}, a1 = a0, a2 = a0, a3 = a0;
; #pragma unroll 16
;     for (int kk = 0; kk < 32; ++kk) { const f32x4 w = *(const f32x4*)(W + (size_t)kk * 6144);
;         a0 += w * scr[kk]; a1 += w * scr[32 + kk]; a2 += w * scr[64 + kk]; a3 += w * scr[96 + kk]; }
.LBB0_61:
	v_lshl_add_u64 v[44:45], v[18:19], 0, s[10:11]
	global_load_dwordx4 v[148:151], v[44:45], off
	v_add_co_u32_e32 v218, vcc, s20, v44
	s_nop 1
	v_addc_co_u32_e32 v219, vcc, 0, v45, vcc
	global_load_dwordx4 v[152:155], v[218:219], off
	v_add_co_u32_e32 v218, vcc, s22, v44
	s_nop 1
	v_addc_co_u32_e32 v219, vcc, 0, v45, vcc
	global_load_dwordx4 v[156:159], v[218:219], off
	v_add_co_u32_e32 v218, vcc, s35, v44
	s_nop 1
	v_addc_co_u32_e32 v219, vcc, 0, v45, vcc
	global_load_dwordx4 v[160:163], v[218:219], off
	v_add_co_u32_e32 v218, vcc, s23, v44
	s_nop 1
	v_addc_co_u32_e32 v219, vcc, 0, v45, vcc
	global_load_dwordx4 v[164:167], v[218:219], off
	v_add_co_u32_e32 v218, vcc, s36, v44
	s_nop 1
	v_addc_co_u32_e32 v219, vcc, 0, v45, vcc
	global_load_dwordx4 v[168:171], v[218:219], off
	v_add_co_u32_e32 v218, vcc, s43, v44
	s_nop 1
	v_addc_co_u32_e32 v219, vcc, 0, v45, vcc
	global_load_dwordx4 v[172:175], v[218:219], off
	v_add_co_u32_e32 v218, vcc, s44, v44
	s_nop 1
	v_addc_co_u32_e32 v219, vcc, 0, v45, vcc
	global_load_dwordx4 v[176:179], v[218:219], off
	v_add_co_u32_e32 v218, vcc, s25, v44
	s_nop 1
	v_addc_co_u32_e32 v219, vcc, 0, v45, vcc
	global_load_dwordx4 v[180:183], v[218:219], off
	v_add_co_u32_e32 v218, vcc, s45, v44
	s_nop 1
	v_addc_co_u32_e32 v219, vcc, 0, v45, vcc
	global_load_dwordx4 v[184:187], v[218:219], off
	v_add_co_u32_e32 v218, vcc, s46, v44
	s_nop 1
	v_addc_co_u32_e32 v219, vcc, 0, v45, vcc
	global_load_dwordx4 v[188:191], v[218:219], off
	v_add_co_u32_e32 v218, vcc, s47, v44
	s_nop 1
	v_addc_co_u32_e32 v219, vcc, 0, v45, vcc
	global_load_dwordx4 v[192:195], v[218:219], off
	v_add_co_u32_e32 v218, vcc, s27, v44
	s_nop 1
	v_addc_co_u32_e32 v219, vcc, 0, v45, vcc
	global_load_dwordx4 v[202:205], v[218:219], off
	v_add_co_u32_e32 v218, vcc, s48, v44
	s_nop 1
	v_addc_co_u32_e32 v219, vcc, 0, v45, vcc
	global_load_dwordx4 v[206:209], v[218:219], off
	v_add_co_u32_e32 v218, vcc, s49, v44
	s_nop 1
	v_addc_co_u32_e32 v219, vcc, 0, v45, vcc
	global_load_dwordx4 v[210:213], v[218:219], off
	v_add_co_u32_e32 v218, vcc, s50, v44
	s_nop 1
	v_addc_co_u32_e32 v219, vcc, 0, v45, vcc
	global_load_dwordx4 v[214:217], v[218:219], off
	s_waitcnt vmcnt(15)
	v_mov_b32_e32 v20, v148
	v_mov_b32_e32 v21, v149
	v_mov_b32_e32 v22, v150
	v_mov_b32_e32 v23, v151
	v_mov_b32_e32 v54, s54
	ds_read_b128 v[24:27], v54
	ds_read_b128 v[28:31], v54 offset:16
	ds_read_b128 v[32:35], v54 offset:32
	ds_read_b128 v[36:39], v54 offset:48
	ds_read_b128 v[40:43], v54 offset:128
	s_add_u32 s10, s10, 0x60000
	s_addc_u32 s11, s11, 0
	s_add_i32 s54, s54, 64
	s_cmp_eq_u32 s10, 0xc0000
	s_waitcnt lgkmcnt(4)
	v_pk_fma_f32 v[46:47], v[22:23], v[24:25], v[4:5] op_sel_hi:[1,0,1]
	v_pk_fma_f32 v[48:49], v[20:21], v[24:25], v[14:15] op_sel_hi:[1,0,1]
	s_waitcnt lgkmcnt(0)
	v_pk_fma_f32 v[50:51], v[22:23], v[40:41], v[2:3] op_sel_hi:[1,0,1]
	v_pk_fma_f32 v[52:53], v[20:21], v[40:41], v[12:13] op_sel_hi:[1,0,1]
	ds_read_b128 v[2:5], v54 offset:256
	ds_read_b128 v[12:15], v54 offset:384
	s_waitcnt lgkmcnt(1)
	v_pk_fma_f32 v[16:17], v[20:21], v[2:3], v[16:17] op_sel_hi:[1,0,1]
	s_waitcnt lgkmcnt(0)
	v_pk_fma_f32 v[10:11], v[20:21], v[12:13], v[10:11] op_sel_hi:[1,0,1]
	v_add_co_u32_e32 v20, vcc, s20, v44
	v_pk_fma_f32 v[6:7], v[22:23], v[2:3], v[6:7] op_sel_hi:[1,0,1]
	s_nop 0
	v_addc_co_u32_e32 v21, vcc, 0, v45, vcc
	v_pk_fma_f32 v[0:1], v[22:23], v[12:13], v[0:1] op_sel_hi:[1,0,1]
	s_waitcnt vmcnt(14)
	v_mov_b32_e32 v20, v152
	v_mov_b32_e32 v21, v153
	v_mov_b32_e32 v22, v154
	v_mov_b32_e32 v23, v155
	v_pk_fma_f32 v[10:11], v[20:21], v[12:13], v[10:11] op_sel:[0,1,0]
	v_pk_fma_f32 v[12:13], v[22:23], v[12:13], v[0:1] op_sel:[0,1,0]
	v_add_co_u32_e32 v0, vcc, s22, v44
	v_pk_fma_f32 v[16:17], v[20:21], v[2:3], v[16:17] op_sel:[0,1,0]
	s_nop 0
	v_addc_co_u32_e32 v1, vcc, 0, v45, vcc
	v_pk_fma_f32 v[6:7], v[22:23], v[2:3], v[6:7] op_sel:[0,1,0]
	s_waitcnt vmcnt(13)
	v_mov_b32_e32 v0, v156
	v_mov_b32_e32 v1, v157
	v_mov_b32_e32 v2, v158
	v_mov_b32_e32 v3, v159
	v_pk_fma_f32 v[48:49], v[20:21], v[24:25], v[48:49] op_sel:[0,1,0]
	v_pk_fma_f32 v[24:25], v[22:23], v[24:25], v[46:47] op_sel:[0,1,0]
	v_pk_fma_f32 v[46:47], v[20:21], v[40:41], v[52:53] op_sel:[0,1,0]
	v_pk_fma_f32 v[40:41], v[22:23], v[40:41], v[50:51] op_sel:[0,1,0]
	v_pk_fma_f32 v[20:21], v[2:3], v[26:27], v[24:25] op_sel_hi:[1,0,1]
	v_pk_fma_f32 v[22:23], v[0:1], v[26:27], v[48:49] op_sel_hi:[1,0,1]
	v_pk_fma_f32 v[24:25], v[2:3], v[42:43], v[40:41] op_sel_hi:[1,0,1]
	v_pk_fma_f32 v[40:41], v[0:1], v[42:43], v[46:47] op_sel_hi:[1,0,1]
	v_pk_fma_f32 v[16:17], v[0:1], v[4:5], v[16:17] op_sel_hi:[1,0,1]
	v_pk_fma_f32 v[10:11], v[0:1], v[14:15], v[10:11] op_sel_hi:[1,0,1]
	v_add_co_u32_e32 v0, vcc, s35, v44
	v_pk_fma_f32 v[6:7], v[2:3], v[4:5], v[6:7] op_sel_hi:[1,0,1]
	s_nop 0
	v_addc_co_u32_e32 v1, vcc, 0, v45, vcc
	v_pk_fma_f32 v[12:13], v[2:3], v[14:15], v[12:13] op_sel_hi:[1,0,1]
	s_waitcnt vmcnt(12)
	v_mov_b32_e32 v0, v160
	v_mov_b32_e32 v1, v161
	v_mov_b32_e32 v2, v162
	v_mov_b32_e32 v3, v163
	v_mov_b32_e32 v4, v27
	v_pk_fma_f32 v[20:21], v[2:3], v[4:5], v[20:21] op_sel_hi:[1,0,1]
	v_pk_fma_f32 v[22:23], v[0:1], v[4:5], v[22:23] op_sel_hi:[1,0,1]
	v_mov_b32_e32 v4, v43
	v_pk_fma_f32 v[24:25], v[2:3], v[4:5], v[24:25] op_sel_hi:[1,0,1]
	v_pk_fma_f32 v[26:27], v[0:1], v[4:5], v[40:41] op_sel_hi:[1,0,1]
	v_mov_b32_e32 v4, v5
	v_pk_fma_f32 v[40:41], v[2:3], v[4:5], v[6:7] op_sel_hi:[1,0,1]
	v_pk_fma_f32 v[16:17], v[0:1], v[4:5], v[16:17] op_sel_hi:[1,0,1]
	v_mov_b32_e32 v4, v15
	v_pk_fma_f32 v[46:47], v[0:1], v[4:5], v[10:11] op_sel_hi:[1,0,1]
	v_add_co_u32_e32 v0, vcc, s23, v44
	v_pk_fma_f32 v[42:43], v[2:3], v[4:5], v[12:13] op_sel_hi:[1,0,1]
	s_nop 0
	v_addc_co_u32_e32 v1, vcc, 0, v45, vcc
	s_waitcnt vmcnt(11)
; __device__ __forceinline__ void gemv_item(const Params& p, unsigned long long* MOD, int it, LAS float* scr, int lane) {
;     ...
;     for (int kk = 0; kk < 32; ++kk) { const f32x4 w = *(const f32x4*)(W + (size_t)kk * 6144);
;         a0 += w * scr[kk]; a1 += w * scr[32 + kk]; a2 += w * scr[64 + kk]; a3 += w * scr[96 + kk]; }
	v_mov_b32_e32 v0, v164
	v_mov_b32_e32 v1, v165
	v_mov_b32_e32 v2, v166
	v_mov_b32_e32 v3, v167
	ds_read_b128 v[4:7], v54 offset:144
	ds_read_b128 v[10:13], v54 offset:272
	s_waitcnt lgkmcnt(0)
	v_pk_fma_f32 v[48:49], v[0:1], v[10:11], v[16:17] op_sel_hi:[1,0,1]
	ds_read_b128 v[14:17], v54 offset:400
	v_pk_fma_f32 v[22:23], v[0:1], v[28:29], v[22:23] op_sel_hi:[1,0,1]
	v_pk_fma_f32 v[26:27], v[0:1], v[4:5], v[26:27] op_sel_hi:[1,0,1]
	v_pk_fma_f32 v[20:21], v[2:3], v[28:29], v[20:21] op_sel_hi:[1,0,1]
	v_pk_fma_f32 v[24:25], v[2:3], v[4:5], v[24:25] op_sel_hi:[1,0,1]
	s_waitcnt lgkmcnt(0)
	v_pk_fma_f32 v[46:47], v[0:1], v[14:15], v[46:47] op_sel_hi:[1,0,1]
	v_add_co_u32_e32 v0, vcc, s36, v44
	v_pk_fma_f32 v[40:41], v[2:3], v[10:11], v[40:41] op_sel_hi:[1,0,1]
	s_nop 0
	v_addc_co_u32_e32 v1, vcc, 0, v45, vcc
	v_pk_fma_f32 v[42:43], v[2:3], v[14:15], v[42:43] op_sel_hi:[1,0,1]
	s_waitcnt vmcnt(10)
	v_mov_b32_e32 v0, v168
	v_mov_b32_e32 v1, v169
	v_mov_b32_e32 v2, v170
	v_mov_b32_e32 v3, v171
	v_pk_fma_f32 v[20:21], v[2:3], v[28:29], v[20:21] op_sel:[0,1,0]
	v_pk_fma_f32 v[22:23], v[0:1], v[28:29], v[22:23] op_sel:[0,1,0]
	v_pk_fma_f32 v[24:25], v[2:3], v[4:5], v[24:25] op_sel:[0,1,0]
	v_pk_fma_f32 v[4:5], v[0:1], v[4:5], v[26:27] op_sel:[0,1,0]
	v_pk_fma_f32 v[26:27], v[2:3], v[10:11], v[40:41] op_sel:[0,1,0]
	v_pk_fma_f32 v[10:11], v[0:1], v[10:11], v[48:49] op_sel:[0,1,0]
	v_pk_fma_f32 v[28:29], v[2:3], v[14:15], v[42:43] op_sel:[0,1,0]
	v_pk_fma_f32 v[14:15], v[0:1], v[14:15], v[46:47] op_sel:[0,1,0]
	v_add_co_u32_e32 v0, vcc, s43, v44
	s_nop 1
	v_addc_co_u32_e32 v1, vcc, 0, v45, vcc
	s_waitcnt vmcnt(9)
	v_mov_b32_e32 v0, v172
	v_mov_b32_e32 v1, v173
	v_mov_b32_e32 v2, v174
	v_mov_b32_e32 v3, v175
	v_pk_fma_f32 v[22:23], v[0:1], v[30:31], v[22:23] op_sel_hi:[1,0,1]
	v_pk_fma_f32 v[4:5], v[0:1], v[6:7], v[4:5] op_sel_hi:[1,0,1]
	v_pk_fma_f32 v[10:11], v[0:1], v[12:13], v[10:11] op_sel_hi:[1,0,1]
	v_pk_fma_f32 v[14:15], v[0:1], v[16:17], v[14:15] op_sel_hi:[1,0,1]
	v_add_co_u32_e32 v0, vcc, s44, v44
	v_pk_fma_f32 v[20:21], v[2:3], v[30:31], v[20:21] op_sel_hi:[1,0,1]
	s_nop 0
	v_addc_co_u32_e32 v1, vcc, 0, v45, vcc
	v_pk_fma_f32 v[24:25], v[2:3], v[6:7], v[24:25] op_sel_hi:[1,0,1]
	v_pk_fma_f32 v[26:27], v[2:3], v[12:13], v[26:27] op_sel_hi:[1,0,1]
	v_pk_fma_f32 v[28:29], v[2:3], v[16:17], v[28:29] op_sel_hi:[1,0,1]
	s_waitcnt vmcnt(8)
	v_mov_b32_e32 v0, v176
	v_mov_b32_e32 v1, v177
	v_mov_b32_e32 v2, v178
	v_mov_b32_e32 v3, v179
	v_mov_b32_e32 v6, v31
	v_pk_fma_f32 v[20:21], v[2:3], v[6:7], v[20:21] op_sel_hi:[1,0,1]
	v_pk_fma_f32 v[22:23], v[0:1], v[6:7], v[22:23] op_sel_hi:[1,0,1]
	v_mov_b32_e32 v6, v7
	v_pk_fma_f32 v[30:31], v[0:1], v[6:7], v[4:5] op_sel_hi:[1,0,1]
	v_mov_b32_e32 v4, v13
	v_pk_fma_f32 v[26:27], v[2:3], v[4:5], v[26:27] op_sel_hi:[1,0,1]
	v_pk_fma_f32 v[40:41], v[0:1], v[4:5], v[10:11] op_sel_hi:[1,0,1]
	v_mov_b32_e32 v4, v17
	v_pk_fma_f32 v[42:43], v[0:1], v[4:5], v[14:15] op_sel_hi:[1,0,1]
	v_add_co_u32_e32 v0, vcc, s25, v44
	v_pk_fma_f32 v[24:25], v[2:3], v[6:7], v[24:25] op_sel_hi:[1,0,1]
	s_nop 0
	v_addc_co_u32_e32 v1, vcc, 0, v45, vcc
	v_pk_fma_f32 v[28:29], v[2:3], v[4:5], v[28:29] op_sel_hi:[1,0,1]
	s_waitcnt vmcnt(7)
	v_mov_b32_e32 v0, v180
	v_mov_b32_e32 v1, v181
	v_mov_b32_e32 v2, v182
	v_mov_b32_e32 v3, v183
	ds_read_b128 v[4:7], v54 offset:160
	ds_read_b128 v[10:13], v54 offset:288
	ds_read_b128 v[14:17], v54 offset:416
	v_pk_fma_f32 v[22:23], v[0:1], v[32:33], v[22:23] op_sel_hi:[1,0,1]
	s_waitcnt lgkmcnt(2)
	v_pk_fma_f32 v[30:31], v[0:1], v[4:5], v[30:31] op_sel_hi:[1,0,1]
	s_waitcnt lgkmcnt(1)
	v_pk_fma_f32 v[40:41], v[0:1], v[10:11], v[40:41] op_sel_hi:[1,0,1]
	s_waitcnt lgkmcnt(0)
	v_pk_fma_f32 v[42:43], v[0:1], v[14:15], v[42:43] op_sel_hi:[1,0,1]
	v_add_co_u32_e32 v0, vcc, s45, v44
	v_pk_fma_f32 v[20:21], v[2:3], v[32:33], v[20:21] op_sel_hi:[1,0,1]
	s_nop 0
	v_addc_co_u32_e32 v1, vcc, 0, v45, vcc
	v_pk_fma_f32 v[24:25], v[2:3], v[4:5], v[24:25] op_sel_hi:[1,0,1]
	v_pk_fma_f32 v[26:27], v[2:3], v[10:11], v[26:27] op_sel_hi:[1,0,1]
	v_pk_fma_f32 v[28:29], v[2:3], v[14:15], v[28:29] op_sel_hi:[1,0,1]
	s_waitcnt vmcnt(6)
	v_mov_b32_e32 v0, v184
	v_mov_b32_e32 v1, v185
	v_mov_b32_e32 v2, v186
	v_mov_b32_e32 v3, v187
	v_pk_fma_f32 v[22:23], v[0:1], v[32:33], v[22:23] op_sel:[0,1,0]
	v_pk_fma_f32 v[24:25], v[2:3], v[4:5], v[24:25] op_sel:[0,1,0]
	v_pk_fma_f32 v[4:5], v[0:1], v[4:5], v[30:31] op_sel:[0,1,0]
	v_pk_fma_f32 v[26:27], v[2:3], v[10:11], v[26:27] op_sel:[0,1,0]
	v_pk_fma_f32 v[10:11], v[0:1], v[10:11], v[40:41] op_sel:[0,1,0]
	v_pk_fma_f32 v[28:29], v[2:3], v[14:15], v[28:29] op_sel:[0,1,0]
	v_pk_fma_f32 v[14:15], v[0:1], v[14:15], v[42:43] op_sel:[0,1,0]
	v_add_co_u32_e32 v0, vcc, s46, v44
	v_pk_fma_f32 v[20:21], v[2:3], v[32:33], v[20:21] op_sel:[0,1,0]
	s_nop 0
	v_addc_co_u32_e32 v1, vcc, 0, v45, vcc
	s_waitcnt vmcnt(5)
; __device__ __forceinline__ void gemv_item(const Params& p, unsigned long long* MOD, int it, LAS float* scr, int lane) {
;     ...
;     for (int kk = 0; kk < 32; ++kk) { const f32x4 w = *(const f32x4*)(W + (size_t)kk * 6144);
;         a0 += w * scr[kk]; a1 += w * scr[32 + kk]; a2 += w * scr[64 + kk]; a3 += w * scr[96 + kk]; }
;     if (ks == 0) { const f32x4 bv = *(const f32x4*)(p.ada_b + mat * 6144 + n0); a0 += bv; a1 += bv; a2 += bv; a3 += bv; }
	v_mov_b32_e32 v0, v188
	v_mov_b32_e32 v1, v189
	v_mov_b32_e32 v2, v190
	v_mov_b32_e32 v3, v191
	v_pk_fma_f32 v[22:23], v[0:1], v[34:35], v[22:23] op_sel_hi:[1,0,1]
	v_pk_fma_f32 v[4:5], v[0:1], v[6:7], v[4:5] op_sel_hi:[1,0,1]
	v_pk_fma_f32 v[10:11], v[0:1], v[12:13], v[10:11] op_sel_hi:[1,0,1]
	v_pk_fma_f32 v[14:15], v[0:1], v[16:17], v[14:15] op_sel_hi:[1,0,1]
	v_add_co_u32_e32 v0, vcc, s47, v44
	v_pk_fma_f32 v[20:21], v[2:3], v[34:35], v[20:21] op_sel_hi:[1,0,1]
	s_nop 0
	v_addc_co_u32_e32 v1, vcc, 0, v45, vcc
	v_pk_fma_f32 v[24:25], v[2:3], v[6:7], v[24:25] op_sel_hi:[1,0,1]
	v_pk_fma_f32 v[26:27], v[2:3], v[12:13], v[26:27] op_sel_hi:[1,0,1]
	v_pk_fma_f32 v[28:29], v[2:3], v[16:17], v[28:29] op_sel_hi:[1,0,1]
	s_waitcnt vmcnt(4)
	v_mov_b32_e32 v0, v192
	v_mov_b32_e32 v1, v193
	v_mov_b32_e32 v2, v194
	v_mov_b32_e32 v3, v195
	v_mov_b32_e32 v6, v35
	v_pk_fma_f32 v[20:21], v[2:3], v[6:7], v[20:21] op_sel_hi:[1,0,1]
	v_pk_fma_f32 v[22:23], v[0:1], v[6:7], v[22:23] op_sel_hi:[1,0,1]
	v_mov_b32_e32 v6, v7
	v_pk_fma_f32 v[30:31], v[0:1], v[6:7], v[4:5] op_sel_hi:[1,0,1]
	v_mov_b32_e32 v4, v13
	v_pk_fma_f32 v[12:13], v[2:3], v[4:5], v[26:27] op_sel_hi:[1,0,1]
	v_pk_fma_f32 v[10:11], v[0:1], v[4:5], v[10:11] op_sel_hi:[1,0,1]
	v_mov_b32_e32 v4, v17
	v_pk_fma_f32 v[26:27], v[2:3], v[4:5], v[28:29] op_sel_hi:[1,0,1]
	v_pk_fma_f32 v[28:29], v[0:1], v[4:5], v[14:15] op_sel_hi:[1,0,1]
	v_add_co_u32_e32 v0, vcc, s27, v44
	v_pk_fma_f32 v[24:25], v[2:3], v[6:7], v[24:25] op_sel_hi:[1,0,1]
	s_nop 0
	v_addc_co_u32_e32 v1, vcc, 0, v45, vcc
	s_waitcnt vmcnt(3)
	v_mov_b32_e32 v0, v202
	v_mov_b32_e32 v1, v203
	v_mov_b32_e32 v2, v204
	v_mov_b32_e32 v3, v205
	ds_read_b128 v[4:7], v54 offset:176
	ds_read_b128 v[14:17], v54 offset:304
	v_pk_fma_f32 v[32:33], v[2:3], v[36:37], v[20:21] op_sel_hi:[1,0,1]
	v_pk_fma_f32 v[34:35], v[0:1], v[36:37], v[22:23] op_sel_hi:[1,0,1]
	ds_read_b128 v[20:23], v54 offset:432
	s_waitcnt lgkmcnt(2)
	v_pk_fma_f32 v[30:31], v[0:1], v[4:5], v[30:31] op_sel_hi:[1,0,1]
	s_waitcnt lgkmcnt(1)
	v_pk_fma_f32 v[10:11], v[0:1], v[14:15], v[10:11] op_sel_hi:[1,0,1]
	v_pk_fma_f32 v[24:25], v[2:3], v[4:5], v[24:25] op_sel_hi:[1,0,1]
	v_pk_fma_f32 v[12:13], v[2:3], v[14:15], v[12:13] op_sel_hi:[1,0,1]
	s_waitcnt lgkmcnt(0)
	v_pk_fma_f32 v[28:29], v[0:1], v[20:21], v[28:29] op_sel_hi:[1,0,1]
	v_add_co_u32_e32 v0, vcc, s48, v44
	v_pk_fma_f32 v[26:27], v[2:3], v[20:21], v[26:27] op_sel_hi:[1,0,1]
	s_nop 0
	v_addc_co_u32_e32 v1, vcc, 0, v45, vcc
	s_waitcnt vmcnt(2)
	v_mov_b32_e32 v0, v206
	v_mov_b32_e32 v1, v207
	v_mov_b32_e32 v2, v208
	v_mov_b32_e32 v3, v209
	v_pk_fma_f32 v[34:35], v[0:1], v[36:37], v[34:35] op_sel:[0,1,0]
	v_pk_fma_f32 v[24:25], v[2:3], v[4:5], v[24:25] op_sel:[0,1,0]
	v_pk_fma_f32 v[4:5], v[0:1], v[4:5], v[30:31] op_sel:[0,1,0]
	v_pk_fma_f32 v[12:13], v[2:3], v[14:15], v[12:13] op_sel:[0,1,0]
	v_pk_fma_f32 v[10:11], v[0:1], v[14:15], v[10:11] op_sel:[0,1,0]
	v_pk_fma_f32 v[14:15], v[2:3], v[20:21], v[26:27] op_sel:[0,1,0]
	v_pk_fma_f32 v[20:21], v[0:1], v[20:21], v[28:29] op_sel:[0,1,0]
	v_add_co_u32_e32 v0, vcc, s49, v44
	v_pk_fma_f32 v[32:33], v[2:3], v[36:37], v[32:33] op_sel:[0,1,0]
	s_nop 0
	v_addc_co_u32_e32 v1, vcc, 0, v45, vcc
	s_waitcnt vmcnt(1)
	v_mov_b32_e32 v0, v210
	v_mov_b32_e32 v1, v211
	v_mov_b32_e32 v2, v212
	v_mov_b32_e32 v3, v213
	v_pk_fma_f32 v[30:31], v[0:1], v[38:39], v[34:35] op_sel_hi:[1,0,1]
	v_pk_fma_f32 v[34:35], v[0:1], v[6:7], v[4:5] op_sel_hi:[1,0,1]
	v_pk_fma_f32 v[10:11], v[0:1], v[16:17], v[10:11] op_sel_hi:[1,0,1]
	v_pk_fma_f32 v[20:21], v[0:1], v[22:23], v[20:21] op_sel_hi:[1,0,1]
	v_add_co_u32_e32 v0, vcc, s50, v44
	v_pk_fma_f32 v[28:29], v[2:3], v[38:39], v[32:33] op_sel_hi:[1,0,1]
	s_nop 0
	v_addc_co_u32_e32 v1, vcc, 0, v45, vcc
	v_pk_fma_f32 v[32:33], v[2:3], v[6:7], v[24:25] op_sel_hi:[1,0,1]
	s_waitcnt vmcnt(0)
	v_mov_b32_e32 v24, v214
	v_mov_b32_e32 v25, v215
	v_mov_b32_e32 v26, v216
	v_mov_b32_e32 v27, v217
	v_mov_b32_e32 v0, v39
	v_pk_fma_f32 v[40:41], v[2:3], v[22:23], v[14:15] op_sel_hi:[1,0,1]
	v_pk_fma_f32 v[36:37], v[2:3], v[16:17], v[12:13] op_sel_hi:[1,0,1]
	v_pk_fma_f32 v[4:5], v[26:27], v[0:1], v[28:29] op_sel_hi:[1,0,1]
	v_pk_fma_f32 v[14:15], v[24:25], v[0:1], v[30:31] op_sel_hi:[1,0,1]
	v_mov_b32_e32 v0, v7
	v_pk_fma_f32 v[2:3], v[26:27], v[0:1], v[32:33] op_sel_hi:[1,0,1]
	v_pk_fma_f32 v[12:13], v[24:25], v[0:1], v[34:35] op_sel_hi:[1,0,1]
	v_mov_b32_e32 v0, v17
	v_pk_fma_f32 v[16:17], v[24:25], v[0:1], v[10:11] op_sel_hi:[1,0,1]
	v_mov_b32_e32 v10, v23
	v_pk_fma_f32 v[6:7], v[26:27], v[0:1], v[36:37] op_sel_hi:[1,0,1]
	v_pk_fma_f32 v[0:1], v[26:27], v[10:11], v[40:41] op_sel_hi:[1,0,1]
	v_pk_fma_f32 v[10:11], v[24:25], v[10:11], v[20:21] op_sel_hi:[1,0,1]
	s_cbranch_scc0 .LBB0_61
	s_cmp_eq_u32 s53, 0
	s_cbranch_scc0 .LBB0_29
	s_mul_i32 s0, s2, 0x1800
	s_ashr_i32 s1, s0, 31
	s_lshl_b64 s[0:1], s[0:1], 2
	s_add_u32 s0, s86, s0
	s_addc_u32 s1, s87, s1
	v_lshl_add_u64 v[18:19], v[8:9], 2, s[0:1]
	global_load_dwordx4 v[18:21], v[18:19], off
	s_waitcnt vmcnt(0)
	v_pk_add_f32 v[4:5], v[4:5], v[20:21]
	v_pk_add_f32 v[14:15], v[14:15], v[18:19]
	v_pk_add_f32 v[2:3], v[2:3], v[20:21]
	v_pk_add_f32 v[12:13], v[12:13], v[18:19]
	v_pk_add_f32 v[6:7], v[6:7], v[20:21]
	v_pk_add_f32 v[16:17], v[16:17], v[18:19]
	v_pk_add_f32 v[0:1], v[0:1], v[20:21]
	v_pk_add_f32 v[10:11], v[10:11], v[18:19]
	s_branch .LBB0_29
